# out-projection epilogue: residual loads of the next row batch issued before the current batch's stores (into dead fragment / consumed accumulator registers); batch waits are vmcnt(8) instead of vmcnt(
# baseline (speedup 1.0000x reference)
; #define PG8_STAGE(bufoff, gbase, voff) do { _Pragma("unroll") for (int _i = 0; _i < 2; ++_i) \
;         __builtin_amdgcn_global_load_lds((const unsigned*)((const char*)(gbase) + (voff)[_i]), (PG8_LAS unsigned*)(lds + (bufoff) + ldsw + _i * 8192), 16, 0, 0); } while (0)
; #define PG8_LDA(dst, b, h) do { _Pragma("unroll") for (int m = 0; m < 4; ++m) _Pragma("unroll") for (int k = 0; k < 2; ++k) dst[m][k] = *(const PG8_LAS bf16x8*)(lds + PG8_SA(b, h) + aoff + m * 2048 + k * 1024); } while (0)
; #define PG8_WAIT_V(n) asm volatile("s_waitcnt vmcnt(" #n ")" ::: "memory")
; template <bool FP8, class Epi, class Sched>
; __device__ __forceinline__ void gemm_phase(PG8_LAS unsigned char* lds, const Gemm g, const Sched& S, const Epi& E) {
;     ...
;         for (int t = 0; t < nt; t += 2) {
;             const bool last = (t == nt - 2);
;             const char* a1 = cA + (size_t)(t + 1) * kstep;
;             const char* a2 = last ? nA : cA + (size_t)(t + 2) * kstep; const char* b2 = last ? nB : cB + (size_t)(t + 2) * kstep;
;             const char* a3 = a2 + kstep; const char* b3 = b2 + kstep;
;             if (last && has_next) S.a_ready(nxt);
;             PG8_LDB(B0, 0, 0); PG8_SCHED; PG8_LDA(At, 0, 0); PG8_STAGE(PG8_SA(1, 1), a1 + hstepA, voffA);
;             PG8_WAIT_L(8); PG8_BAR; PG8_WAIT_L(0); PG8_MMA(0, 0, At, B0); PG8_BAR; PG8_SCHED;
;             PG8_LDB(B1, 0, 1); PG8_STAGE(PG8_SB(0, 0), b2, voffB);
;             PG8_BAR; PG8_WAIT_L(0); PG8_MMA(0, 1, At, B1); PG8_BAR;
;             PG8_LDA(At, 0, 1); PG8_STAGE(PG8_SA(0, 0), a2, voffA);
;             PG8_BAR; PG8_WAIT_L(0); PG8_MMA(1, 0, At, B0); PG8_BAR; PG8_SCHED;
;             PG8_STAGE(PG8_SB(0, 1), b2 + hstep, voffB);
;             PG8_WAIT_V(6); PG8_BAR; PG8_MMA(1, 1, At, B1); PG8_BAR;
;             PG8_LDB(B0, 1, 0); PG8_SCHED; PG8_LDA(At, 1, 0); PG8_STAGE(PG8_SA(0, 1), a2 + hstepA, voffA);
;             PG8_WAIT_L(8); PG8_BAR; PG8_WAIT_L(0); PG8_MMA(0, 0, At, B0); PG8_BAR; PG8_SCHED;
;             PG8_LDB(B1, 1, 1); PG8_STAGE(PG8_SB(1, 0), b3, voffB);
;             PG8_BAR; PG8_WAIT_L(0); PG8_MMA(0, 1, At, B1); PG8_BAR;
;             PG8_LDA(At, 1, 1); PG8_STAGE(PG8_SA(1, 0), a3, voffA);
;             PG8_BAR; PG8_WAIT_L(0); PG8_MMA(1, 0, At, B0); PG8_BAR; PG8_SCHED;
;             PG8_STAGE(PG8_SB(1, 1), b3 + hstep, voffB);
;             PG8_WAIT_V(6); PG8_BAR; PG8_MMA(1, 1, At, B1); PG8_BAR;
.LBB0_1543:
	s_add_u32 s12, s16, 0x100
	s_addc_u32 s13, s17, 0
	s_add_i32 s30, 0, 0x10000
	v_add_u32_e32 v6, s30, v170
	ds_read_b128 v[10:13], v6
	ds_read_b128 v[14:17], v6 offset:1024
	ds_read_b128 v[2:5], v6 offset:2048
	ds_read_b128 v[6:9], v6 offset:3072
	s_cmp_eq_u32 s72, 20
	s_cselect_b32 s19, s1, s13
	s_cselect_b32 s18, s0, s12
	s_cselect_b32 s15, s11, s71
	s_cselect_b32 s14, s10, s70
	v_lshl_add_u64 v[18:19], s[16:17], 0, v[156:157]
	s_add_i32 m0, s24, 0xc000
	ds_read_b128 v[182:185], v172
	ds_read_b128 v[186:189], v172 offset:1024
	ds_read_b128 v[190:193], v172 offset:2048
	ds_read_b128 v[194:197], v172 offset:3072
	ds_read_b128 v[198:201], v172 offset:4096
	ds_read_b128 v[202:205], v172 offset:5120
	ds_read_b128 v[206:209], v172 offset:6144
	ds_read_b128 v[210:213], v172 offset:7168
	global_load_lds_dwordx4 v[18:19], off
	v_lshl_add_u64 v[18:19], s[16:17], 0, v[158:159]
	s_add_i32 m0, s24, 0xe000
	s_nop 0
	global_load_lds_dwordx4 v[18:19], off
	s_waitcnt lgkmcnt(8)
	s_barrier
	s_waitcnt lgkmcnt(0)
	s_setprio 1
	s_waitcnt lgkmcnt(0)
	s_nop 1
	v_mfma_scale_f32_16x16x128_f8f6f4 v[150:153], v[10:17], v[182:189], v[150:153], v168, v168 op_sel_hi:[0,0,0]
	s_nop 1
	v_mfma_scale_f32_16x16x128_f8f6f4 v[146:149], v[2:9], v[182:189], v[146:149], v168, v168 op_sel_hi:[0,0,0]
	s_nop 1
	v_mfma_scale_f32_16x16x128_f8f6f4 v[142:145], v[10:17], v[190:197], v[142:145], v168, v168 op_sel_hi:[0,0,0]
	s_nop 1
	v_mfma_scale_f32_16x16x128_f8f6f4 v[138:141], v[2:9], v[190:197], v[138:141], v168, v168 op_sel_hi:[0,0,0]
	s_nop 1
	v_mfma_scale_f32_16x16x128_f8f6f4 v[118:121], v[10:17], v[198:205], v[118:121], v168, v168 op_sel_hi:[0,0,0]
	s_nop 1
	v_mfma_scale_f32_16x16x128_f8f6f4 v[114:117], v[2:9], v[198:205], v[114:117], v168, v168 op_sel_hi:[0,0,0]
	s_nop 1
	v_mfma_scale_f32_16x16x128_f8f6f4 v[110:113], v[10:17], v[206:213], v[110:113], v168, v168 op_sel_hi:[0,0,0]
	s_nop 1
	v_mfma_scale_f32_16x16x128_f8f6f4 v[106:109], v[2:9], v[206:213], v[106:109], v168, v168 op_sel_hi:[0,0,0]
	s_setprio 0
	s_barrier
	s_add_i32 s31, 0, 0x14000
	s_add_i32 s16, s30, s23
	v_add_u32_e32 v22, s31, v170
	v_lshl_add_u64 v[160:161], s[14:15], 0, v[0:1]
	s_mov_b32 m0, s16
	ds_read_b128 v[236:239], v22
	ds_read_b128 v[240:243], v22 offset:1024
	ds_read_b128 v[18:21], v22 offset:2048
	ds_read_b128 v[22:25], v22 offset:3072
	global_load_lds_dwordx4 v[160:161], off
	v_lshl_add_u64 v[162:163], s[14:15], 0, v[154:155]
	s_add_i32 m0, s16, 0x2000
	s_nop 0
	global_load_lds_dwordx4 v[162:163], off
	s_barrier
	s_waitcnt lgkmcnt(0)
	s_setprio 1
	s_waitcnt lgkmcnt(0)
	s_nop 1
	v_mfma_scale_f32_16x16x128_f8f6f4 v[134:137], v[236:243], v[182:189], v[134:137], v168, v168 op_sel_hi:[0,0,0]
	s_nop 1
	v_mfma_scale_f32_16x16x128_f8f6f4 v[130:133], v[18:25], v[182:189], v[130:133], v168, v168 op_sel_hi:[0,0,0]
	s_nop 1
	v_mfma_scale_f32_16x16x128_f8f6f4 v[126:129], v[236:243], v[190:197], v[126:129], v168, v168 op_sel_hi:[0,0,0]
	s_nop 1
	v_mfma_scale_f32_16x16x128_f8f6f4 v[122:125], v[18:25], v[190:197], v[122:125], v168, v168 op_sel_hi:[0,0,0]
	s_nop 1
	v_mfma_scale_f32_16x16x128_f8f6f4 v[102:105], v[236:243], v[198:205], v[102:105], v168, v168 op_sel_hi:[0,0,0]
	s_nop 1
	v_mfma_scale_f32_16x16x128_f8f6f4 v[98:101], v[18:25], v[198:205], v[98:101], v168, v168 op_sel_hi:[0,0,0]
	s_nop 1
	v_mfma_scale_f32_16x16x128_f8f6f4 v[94:97], v[236:243], v[206:213], v[94:97], v168, v168 op_sel_hi:[0,0,0]
	s_nop 1
	v_mfma_scale_f32_16x16x128_f8f6f4 v[90:93], v[18:25], v[206:213], v[90:93], v168, v168 op_sel_hi:[0,0,0]
	s_setprio 0
	s_mov_b32 m0, s24
	v_lshl_add_u64 v[164:165], s[18:19], 0, v[0:1]
	s_barrier
	ds_read_b128 v[182:185], v172 offset:16384
	ds_read_b128 v[186:189], v172 offset:17408
	ds_read_b128 v[190:193], v172 offset:18432
	ds_read_b128 v[194:197], v172 offset:19456
	ds_read_b128 v[198:201], v172 offset:20480
	ds_read_b128 v[202:205], v172 offset:21504
	ds_read_b128 v[206:209], v172 offset:22528
	ds_read_b128 v[210:213], v172 offset:23552
	global_load_lds_dwordx4 v[164:165], off
	v_lshl_add_u64 v[166:167], s[18:19], 0, v[154:155]
	s_mov_b32 m0, s25
	s_nop 0
	global_load_lds_dwordx4 v[166:167], off
	s_barrier
	s_waitcnt lgkmcnt(0)
	s_setprio 1
	s_waitcnt lgkmcnt(0)
	s_nop 1
	v_mfma_scale_f32_16x16x128_f8f6f4 v[86:89], v[10:17], v[182:189], v[86:89], v168, v168 op_sel_hi:[0,0,0]
	s_nop 1
	v_mfma_scale_f32_16x16x128_f8f6f4 v[82:85], v[2:9], v[182:189], v[82:85], v168, v168 op_sel_hi:[0,0,0]
	s_nop 1
	v_mfma_scale_f32_16x16x128_f8f6f4 v[78:81], v[10:17], v[190:197], v[78:81], v168, v168 op_sel_hi:[0,0,0]
	s_nop 1
	v_mfma_scale_f32_16x16x128_f8f6f4 v[74:77], v[2:9], v[190:197], v[74:77], v168, v168 op_sel_hi:[0,0,0]
	s_nop 1
	v_mfma_scale_f32_16x16x128_f8f6f4 v[54:57], v[10:17], v[198:205], v[54:57], v168, v168 op_sel_hi:[0,0,0]
	s_nop 1
	v_mfma_scale_f32_16x16x128_f8f6f4 v[50:53], v[2:9], v[198:205], v[50:53], v168, v168 op_sel_hi:[0,0,0]
	s_nop 1
	v_mfma_scale_f32_16x16x128_f8f6f4 v[46:49], v[10:17], v[206:213], v[46:49], v168, v168 op_sel_hi:[0,0,0]
	s_nop 1
	v_mfma_scale_f32_16x16x128_f8f6f4 v[42:45], v[2:9], v[206:213], v[42:45], v168, v168 op_sel_hi:[0,0,0]
	s_setprio 0
	s_barrier
	s_add_u32 s16, s14, 0x60000
	s_addc_u32 s17, s15, 0
	s_add_i32 s30, s31, s23
	v_lshl_add_u64 v[2:3], s[16:17], 0, v[0:1]
	s_mov_b32 m0, s30
	s_nop 0
	global_load_lds_dwordx4 v[2:3], off
	v_lshl_add_u64 v[2:3], s[16:17], 0, v[154:155]
	s_add_i32 m0, s30, 0x2000
	s_nop 0
	global_load_lds_dwordx4 v[2:3], off
	s_waitcnt vmcnt(6)
	s_barrier
; #define PG8_STAGE(bufoff, gbase, voff) do { _Pragma("unroll") for (int _i = 0; _i < 2; ++_i) \
;         __builtin_amdgcn_global_load_lds((const unsigned*)((const char*)(gbase) + (voff)[_i]), (PG8_LAS unsigned*)(lds + (bufoff) + ldsw + _i * 8192), 16, 0, 0); } while (0)
; #define PG8_LDA(dst, b, h) do { _Pragma("unroll") for (int m = 0; m < 4; ++m) _Pragma("unroll") for (int k = 0; k < 2; ++k) dst[m][k] = *(const PG8_LAS bf16x8*)(lds + PG8_SA(b, h) + aoff + m * 2048 + k * 1024); } while (0)
; #define PG8_WAIT_V(n) asm volatile("s_waitcnt vmcnt(" #n ")" ::: "memory")
; template <bool FP8, class Epi, class Sched>
; __device__ __forceinline__ void gemm_phase(PG8_LAS unsigned char* lds, const Gemm g, const Sched& S, const Epi& E) {
;     ...
;         for (int t = 0; t < nt; t += 2) {
;             const bool last = (t == nt - 2);
;             const char* a1 = cA + (size_t)(t + 1) * kstep;
;             const char* a2 = last ? nA : cA + (size_t)(t + 2) * kstep; const char* b2 = last ? nB : cB + (size_t)(t + 2) * kstep;
;             const char* a3 = a2 + kstep; const char* b3 = b2 + kstep;
;             if (last && has_next) S.a_ready(nxt);
;             PG8_LDB(B0, 0, 0); PG8_SCHED; PG8_LDA(At, 0, 0); PG8_STAGE(PG8_SA(1, 1), a1 + hstepA, voffA);
;             PG8_WAIT_L(8); PG8_BAR; PG8_WAIT_L(0); PG8_MMA(0, 0, At, B0); PG8_BAR; PG8_SCHED;
;             PG8_LDB(B1, 0, 1); PG8_STAGE(PG8_SB(0, 0), b2, voffB);
;             PG8_BAR; PG8_WAIT_L(0); PG8_MMA(0, 1, At, B1); PG8_BAR;
;             PG8_LDA(At, 0, 1); PG8_STAGE(PG8_SA(0, 0), a2, voffA);
;             PG8_BAR; PG8_WAIT_L(0); PG8_MMA(1, 0, At, B0); PG8_BAR; PG8_SCHED;
;             PG8_STAGE(PG8_SB(0, 1), b2 + hstep, voffB);
;             PG8_WAIT_V(6); PG8_BAR; PG8_MMA(1, 1, At, B1); PG8_BAR;
;             PG8_LDB(B0, 1, 0); PG8_SCHED; PG8_LDA(At, 1, 0); PG8_STAGE(PG8_SA(0, 1), a2 + hstepA, voffA);
;             PG8_WAIT_L(8); PG8_BAR; PG8_WAIT_L(0); PG8_MMA(0, 0, At, B0); PG8_BAR; PG8_SCHED;
;             PG8_LDB(B1, 1, 1); PG8_STAGE(PG8_SB(1, 0), b3, voffB);
;             PG8_BAR; PG8_WAIT_L(0); PG8_MMA(0, 1, At, B1); PG8_BAR;
;             PG8_LDA(At, 1, 1); PG8_STAGE(PG8_SA(1, 0), a3, voffA);
;             PG8_BAR; PG8_WAIT_L(0); PG8_MMA(1, 0, At, B0); PG8_BAR; PG8_SCHED;
;             PG8_STAGE(PG8_SB(1, 1), b3 + hstep, voffB);
;             PG8_WAIT_V(6); PG8_BAR; PG8_MMA(1, 1, At, B1); PG8_BAR;
	s_setprio 1
	s_nop 1
	v_mfma_scale_f32_16x16x128_f8f6f4 v[70:73], v[236:243], v[182:189], v[70:73], v168, v168 op_sel_hi:[0,0,0]
	s_nop 1
	v_mfma_scale_f32_16x16x128_f8f6f4 v[66:69], v[18:25], v[182:189], v[66:69], v168, v168 op_sel_hi:[0,0,0]
	s_nop 1
	v_mfma_scale_f32_16x16x128_f8f6f4 v[62:65], v[236:243], v[190:197], v[62:65], v168, v168 op_sel_hi:[0,0,0]
	s_nop 1
	v_mfma_scale_f32_16x16x128_f8f6f4 v[58:61], v[18:25], v[190:197], v[58:61], v168, v168 op_sel_hi:[0,0,0]
	s_nop 1
	v_mfma_scale_f32_16x16x128_f8f6f4 v[38:41], v[236:243], v[198:205], v[38:41], v168, v168 op_sel_hi:[0,0,0]
	s_nop 1
	v_mfma_scale_f32_16x16x128_f8f6f4 v[34:37], v[18:25], v[198:205], v[34:37], v168, v168 op_sel_hi:[0,0,0]
	s_nop 1
	v_mfma_scale_f32_16x16x128_f8f6f4 v[30:33], v[236:243], v[206:213], v[30:33], v168, v168 op_sel_hi:[0,0,0]
	s_nop 1
	v_mfma_scale_f32_16x16x128_f8f6f4 v[26:29], v[18:25], v[206:213], v[26:29], v168, v168 op_sel_hi:[0,0,0]
	s_setprio 0
	s_add_i32 s30, 0, 0x18000
	v_add_u32_e32 v14, s30, v170
	s_barrier
	ds_read_b128 v[2:5], v14
	ds_read_b128 v[6:9], v14 offset:1024
	ds_read_b128 v[10:13], v14 offset:2048
	ds_read_b128 v[14:17], v14 offset:3072
	s_add_u32 s16, s18, 0x60000
	s_addc_u32 s17, s19, 0
	s_mov_b32 m0, s26
	v_lshl_add_u64 v[174:175], s[16:17], 0, v[0:1]
	ds_read_b128 v[18:21], v172 offset:32768
	ds_read_b128 v[22:25], v172 offset:33792
	ds_read_b128 v[182:185], v172 offset:34816
	ds_read_b128 v[186:189], v172 offset:35840
	ds_read_b128 v[190:193], v172 offset:36864
	ds_read_b128 v[194:197], v172 offset:37888
	ds_read_b128 v[198:201], v172 offset:38912
	ds_read_b128 v[202:205], v172 offset:39936
	global_load_lds_dwordx4 v[174:175], off
	v_lshl_add_u64 v[174:175], s[16:17], 0, v[154:155]
	s_mov_b32 m0, s27
	s_nop 0
	global_load_lds_dwordx4 v[174:175], off
	s_waitcnt lgkmcnt(8)
	s_barrier
	s_waitcnt lgkmcnt(0)
	s_setprio 1
	s_waitcnt lgkmcnt(0)
	s_nop 1
	v_mfma_scale_f32_16x16x128_f8f6f4 v[150:153], v[2:9], v[18:25], v[150:153], v168, v168 op_sel_hi:[0,0,0]
	s_nop 1
	v_mfma_scale_f32_16x16x128_f8f6f4 v[146:149], v[10:17], v[18:25], v[146:149], v168, v168 op_sel_hi:[0,0,0]
	s_nop 1
	v_mfma_scale_f32_16x16x128_f8f6f4 v[142:145], v[2:9], v[182:189], v[142:145], v168, v168 op_sel_hi:[0,0,0]
	s_nop 1
	v_mfma_scale_f32_16x16x128_f8f6f4 v[138:141], v[10:17], v[182:189], v[138:141], v168, v168 op_sel_hi:[0,0,0]
	s_nop 1
	v_mfma_scale_f32_16x16x128_f8f6f4 v[118:121], v[2:9], v[190:197], v[118:121], v168, v168 op_sel_hi:[0,0,0]
	s_nop 1
	v_mfma_scale_f32_16x16x128_f8f6f4 v[114:117], v[10:17], v[190:197], v[114:117], v168, v168 op_sel_hi:[0,0,0]
	s_nop 1
	v_mfma_scale_f32_16x16x128_f8f6f4 v[110:113], v[2:9], v[198:205], v[110:113], v168, v168 op_sel_hi:[0,0,0]
	s_nop 1
	v_mfma_scale_f32_16x16x128_f8f6f4 v[106:109], v[10:17], v[198:205], v[106:109], v168, v168 op_sel_hi:[0,0,0]
	s_setprio 0
	s_barrier
	s_add_i32 s16, 0, 0x1c000
	s_add_i32 s17, s30, s23
	v_add_u32_e32 v173, s16, v170
	v_lshl_add_u64 v[160:161], v[160:161], 0, s[56:57]
	s_mov_b32 m0, s17
	ds_read_b128 v[206:209], v173
	ds_read_b128 v[210:213], v173 offset:1024
	ds_read_b128 v[236:239], v173 offset:2048
	ds_read_b128 v[240:243], v173 offset:3072
	global_load_lds_dwordx4 v[160:161], off
	v_lshl_add_u64 v[160:161], v[162:163], 0, s[56:57]
	s_add_i32 m0, s17, 0x2000
	s_nop 0
	global_load_lds_dwordx4 v[160:161], off
	s_barrier
	s_waitcnt lgkmcnt(0)
	s_setprio 1
	s_waitcnt lgkmcnt(0)
	s_nop 1
	v_mfma_scale_f32_16x16x128_f8f6f4 v[134:137], v[206:213], v[18:25], v[134:137], v168, v168 op_sel_hi:[0,0,0]
	s_nop 1
	v_mfma_scale_f32_16x16x128_f8f6f4 v[130:133], v[236:243], v[18:25], v[130:133], v168, v168 op_sel_hi:[0,0,0]
	s_nop 1
	v_mfma_scale_f32_16x16x128_f8f6f4 v[126:129], v[206:213], v[182:189], v[126:129], v168, v168 op_sel_hi:[0,0,0]
	s_nop 1
	v_mfma_scale_f32_16x16x128_f8f6f4 v[122:125], v[236:243], v[182:189], v[122:125], v168, v168 op_sel_hi:[0,0,0]
	s_nop 1
	v_mfma_scale_f32_16x16x128_f8f6f4 v[102:105], v[206:213], v[190:197], v[102:105], v168, v168 op_sel_hi:[0,0,0]
	s_nop 1
	v_mfma_scale_f32_16x16x128_f8f6f4 v[98:101], v[236:243], v[190:197], v[98:101], v168, v168 op_sel_hi:[0,0,0]
	s_nop 1
	v_mfma_scale_f32_16x16x128_f8f6f4 v[94:97], v[206:213], v[198:205], v[94:97], v168, v168 op_sel_hi:[0,0,0]
	s_nop 1
	v_mfma_scale_f32_16x16x128_f8f6f4 v[90:93], v[236:243], v[198:205], v[90:93], v168, v168 op_sel_hi:[0,0,0]
	s_setprio 0
	s_mov_b32 m0, s54
	v_lshl_add_u64 v[160:161], v[164:165], 0, s[56:57]
	s_barrier
	ds_read_b128 v[18:21], v172 offset:49152
	ds_read_b128 v[22:25], v172 offset:50176
	ds_read_b128 v[182:185], v172 offset:51200
	ds_read_b128 v[186:189], v172 offset:52224
	ds_read_b128 v[190:193], v172 offset:53248
	ds_read_b128 v[194:197], v172 offset:54272
	ds_read_b128 v[198:201], v172 offset:55296
	ds_read_b128 v[202:205], v172 offset:56320
	global_load_lds_dwordx4 v[160:161], off
	v_lshl_add_u64 v[160:161], v[166:167], 0, s[56:57]
	s_mov_b32 m0, s66
	s_nop 0
	global_load_lds_dwordx4 v[160:161], off
	s_barrier
	s_waitcnt lgkmcnt(0)
	s_setprio 1
	s_waitcnt lgkmcnt(0)
	s_nop 1
	v_mfma_scale_f32_16x16x128_f8f6f4 v[86:89], v[2:9], v[18:25], v[86:89], v168, v168 op_sel_hi:[0,0,0]
	s_nop 1
	v_mfma_scale_f32_16x16x128_f8f6f4 v[82:85], v[10:17], v[18:25], v[82:85], v168, v168 op_sel_hi:[0,0,0]
	s_nop 1
	v_mfma_scale_f32_16x16x128_f8f6f4 v[78:81], v[2:9], v[182:189], v[78:81], v168, v168 op_sel_hi:[0,0,0]
	s_nop 1
	v_mfma_scale_f32_16x16x128_f8f6f4 v[74:77], v[10:17], v[182:189], v[74:77], v168, v168 op_sel_hi:[0,0,0]
	s_nop 1
	v_mfma_scale_f32_16x16x128_f8f6f4 v[54:57], v[2:9], v[190:197], v[54:57], v168, v168 op_sel_hi:[0,0,0]
	s_nop 1
	v_mfma_scale_f32_16x16x128_f8f6f4 v[50:53], v[10:17], v[190:197], v[50:53], v168, v168 op_sel_hi:[0,0,0]
	s_nop 1
	v_mfma_scale_f32_16x16x128_f8f6f4 v[46:49], v[2:9], v[198:205], v[46:49], v168, v168 op_sel_hi:[0,0,0]
	s_nop 1
	v_mfma_scale_f32_16x16x128_f8f6f4 v[42:45], v[10:17], v[198:205], v[42:45], v168, v168 op_sel_hi:[0,0,0]
	s_setprio 0
	s_barrier
; #define PG8_STAGE(bufoff, gbase, voff) do { _Pragma("unroll") for (int _i = 0; _i < 2; ++_i) \
;         __builtin_amdgcn_global_load_lds((const unsigned*)((const char*)(gbase) + (voff)[_i]), (PG8_LAS unsigned*)(lds + (bufoff) + ldsw + _i * 8192), 16, 0, 0); } while (0)
; #define PG8_WAIT_V(n) asm volatile("s_waitcnt vmcnt(" #n ")" ::: "memory")
; #define PG8_WAIT_L(n) asm volatile("s_waitcnt lgkmcnt(" #n ")" ::: "memory")
; #define PG8_BAR __builtin_amdgcn_s_barrier()
; template <bool FP8, class Epi, class Sched>
; __device__ __forceinline__ void gemm_phase(PG8_LAS unsigned char* lds, const Gemm g, const Sched& S, const Epi& E) {
;     ...
;             PG8_WAIT_V(6); PG8_BAR; PG8_MMA(1, 1, At, B1); PG8_BAR;
;             PG8_LDB(B0, 1, 0); PG8_SCHED; PG8_LDA(At, 1, 0); PG8_STAGE(PG8_SA(0, 1), a2 + hstepA, voffA);
;             PG8_WAIT_L(8); PG8_BAR; PG8_WAIT_L(0); PG8_MMA(0, 0, At, B0); PG8_BAR; PG8_SCHED;
;             PG8_LDB(B1, 1, 1); PG8_STAGE(PG8_SB(1, 0), b3, voffB);
;             PG8_BAR; PG8_WAIT_L(0); PG8_MMA(0, 1, At, B1); PG8_BAR;
;             PG8_LDA(At, 1, 1); PG8_STAGE(PG8_SA(1, 0), a3, voffA);
;             PG8_BAR; PG8_WAIT_L(0); PG8_MMA(1, 0, At, B0); PG8_BAR; PG8_SCHED;
;             PG8_STAGE(PG8_SB(1, 1), b3 + hstep, voffB);
;             PG8_WAIT_V(6); PG8_BAR; PG8_MMA(1, 1, At, B1); PG8_BAR;
;   DI void operator()(const f32x4 (&acc)[2][2][4][2], const pg8::Unit& u, int wr, int wc, int fr, int fq) const {
;     const int row0 = u.pm * 256 + wr * 64 + fr, col0 = u.pn * 256 + wc * 32 + 4 * fq;
; #pragma unroll
;     for (int ai = 0; ai < 2; ++ai)
; #pragma unroll
;       for (int mp = 0; mp < 2; ++mp) {
;         f32x4 xv[2][2][2];
; #pragma unroll
;         for (int mm = 0; mm < 2; ++mm)
; #pragma unroll
;           for (int bj = 0; bj < 2; ++bj)
; #pragma unroll
;             for (int n = 0; n < 2; ++n)
;               xv[mm][bj][n] = *(const f32x4*)(xin + (size_t)(row0 + ai * 128 + (mp * 2 + mm) * 16) * 2048 + col0 + bj * 128 + n * 16);
; #pragma unroll
;         for (int mm = 0; mm < 2; ++mm)
; #pragma unroll
;           for (int bj = 0; bj < 2; ++bj)
; #pragma unroll
;             for (int n = 0; n < 2; ++n)
;               *(f32x4*)(xout + (size_t)(row0 + ai * 128 + (mp * 2 + mm) * 16) * 2048 + col0 + bj * 128 + n * 16) = xv[mm][bj][n] + acc[ai][bj][mp * 2 + mm][n] * sc;
;         asm volatile("" ::: "memory");
;       }
	s_add_u32 s14, s14, 0x60080
	s_addc_u32 s15, s15, 0
	s_add_i32 s16, s16, s23
	v_lshl_add_u64 v[2:3], s[14:15], 0, v[0:1]
	s_mov_b32 m0, s16
	s_nop 0
	global_load_lds_dwordx4 v[2:3], off
	v_lshl_add_u64 v[2:3], s[14:15], 0, v[154:155]
	s_add_i32 m0, s16, 0x2000
	s_nop 0
	global_load_lds_dwordx4 v[2:3], off
	s_waitcnt vmcnt(6)
	s_barrier
	s_setprio 1
	s_nop 1
	v_mfma_scale_f32_16x16x128_f8f6f4 v[70:73], v[206:213], v[18:25], v[70:73], v168, v168 op_sel_hi:[0,0,0]
	s_nop 1
	v_mfma_scale_f32_16x16x128_f8f6f4 v[66:69], v[236:243], v[18:25], v[66:69], v168, v168 op_sel_hi:[0,0,0]
	s_nop 1
	v_mfma_scale_f32_16x16x128_f8f6f4 v[62:65], v[206:213], v[182:189], v[62:65], v168, v168 op_sel_hi:[0,0,0]
	s_nop 1
	v_mfma_scale_f32_16x16x128_f8f6f4 v[58:61], v[236:243], v[182:189], v[58:61], v168, v168 op_sel_hi:[0,0,0]
	s_nop 1
	v_mfma_scale_f32_16x16x128_f8f6f4 v[38:41], v[206:213], v[190:197], v[38:41], v168, v168 op_sel_hi:[0,0,0]
	s_nop 1
	v_mfma_scale_f32_16x16x128_f8f6f4 v[34:37], v[236:243], v[190:197], v[34:37], v168, v168 op_sel_hi:[0,0,0]
	s_nop 1
	v_mfma_scale_f32_16x16x128_f8f6f4 v[30:33], v[206:213], v[198:205], v[30:33], v168, v168 op_sel_hi:[0,0,0]
	s_nop 1
	v_mfma_scale_f32_16x16x128_f8f6f4 v[26:29], v[236:243], v[198:205], v[26:29], v168, v168 op_sel_hi:[0,0,0]
	s_setprio 0
	s_add_i32 s72, s72, 2
	s_add_u32 s70, s70, 0x100
	s_addc_u32 s71, s71, 0
	s_cmp_gt_u32 s72, 21
	s_mov_b64 s[16:17], s[12:13]
	s_barrier
	s_cbranch_scc0 .LBB0_1543
	v_lshl_or_b32 v2, s28, 8, v171
	v_lshl_add_u32 v8, s29, 8, v169
	v_ashrrev_i32_e32 v3, 31, v2
	v_readlane_b32 s12, v254, 47
	v_lshlrev_b64 v[2:3], 2, v[2:3]
	v_readlane_b32 s13, v254, 48
	v_ashrrev_i32_e32 v9, 31, v8
	v_lshlrev_b64 v[6:7], 13, v[8:9]
	v_lshl_add_u64 v[4:5], s[12:13], 0, v[2:3]
	v_mov_b32_e32 v214, v8
	v_mov_b32_e32 v216, v4
	v_mov_b32_e32 v217, v5
	s_nop 15
	s_nop 15
	v_lshl_add_u64 v[22:23], v[4:5], 0, v[6:7]
	global_load_dwordx4 v[10:13], v[22:23], off
	global_load_dwordx4 v[14:17], v[22:23], off offset:64
	global_load_dwordx4 v[18:21], v[22:23], off offset:512
	s_nop 0
	global_load_dwordx4 v[22:25], v[22:23], off offset:576
	v_or_b32_e32 v160, 16, v8
	v_ashrrev_i32_e32 v161, 31, v160
	v_lshlrev_b64 v[174:175], 13, v[160:161]
	v_lshl_add_u64 v[186:187], v[4:5], 0, v[174:175]
	global_load_dwordx4 v[160:163], v[186:187], off
	global_load_dwordx4 v[164:167], v[186:187], off offset:64
	global_load_dwordx4 v[182:185], v[186:187], off offset:512
	s_nop 0
	global_load_dwordx4 v[186:189], v[186:187], off offset:576
	s_mov_b64 s[12:13], 0x120000
	s_and_b64 vcc, exec, s[8:9]
	s_mov_b32 s28, s68
	s_mov_b32 s29, s69
	s_mov_b64 s[16:17], s[0:1]
	s_waitcnt vmcnt(0)
	v_add_u32_e32 v202, 32, v214
	v_lshlrev_b32_e32 v202, 13, v202
	v_mov_b32_e32 v203, 0
	v_lshl_add_u64 v[202:203], v[216:217], 0, v[202:203]
	global_load_dwordx4 v[190:193], v[202:203], off
	global_load_dwordx4 v[194:197], v[202:203], off offset:64
	global_load_dwordx4 v[198:201], v[202:203], off offset:512
	s_nop 0
	global_load_dwordx4 v[202:205], v[202:203], off offset:576
	v_add_u32_e32 v240, 48, v214
	v_lshlrev_b32_e32 v240, 13, v240
	v_mov_b32_e32 v241, 0
	v_lshl_add_u64 v[240:241], v[216:217], 0, v[240:241]
	global_load_dwordx4 v[206:209], v[240:241], off
	global_load_dwordx4 v[210:213], v[240:241], off offset:64
	global_load_dwordx4 v[236:239], v[240:241], off offset:512
	s_nop 0
	global_load_dwordx4 v[240:243], v[240:241], off offset:576
	v_pk_fma_f32 v[10:11], v[150:151], s[88:89], v[10:11] op_sel_hi:[1,0,1]
	v_lshl_add_u64 v[150:151], s[80:81], 0, v[6:7]
	v_pk_fma_f32 v[12:13], v[152:153], s[88:89], v[12:13] op_sel_hi:[1,0,1]
	v_lshl_add_u64 v[150:151], v[150:151], 0, v[2:3]
	global_store_dwordx4 v[150:151], v[10:13], off
	s_nop 1
	v_pk_fma_f32 v[12:13], v[148:149], s[88:89], v[16:17] op_sel_hi:[1,0,1]
	v_pk_fma_f32 v[10:11], v[146:147], s[88:89], v[14:15] op_sel_hi:[1,0,1]
	global_store_dwordx4 v[150:151], v[10:13], off offset:64
	v_lshl_add_u64 v[14:15], s[80:81], 0, v[174:175]
	v_lshl_add_u64 v[14:15], v[14:15], 0, v[2:3]
	v_pk_fma_f32 v[12:13], v[136:137], s[88:89], v[20:21] op_sel_hi:[1,0,1]
	v_pk_fma_f32 v[10:11], v[134:135], s[88:89], v[18:19] op_sel_hi:[1,0,1]
	global_store_dwordx4 v[150:151], v[10:13], off offset:512
	s_nop 1
	v_pk_fma_f32 v[12:13], v[132:133], s[88:89], v[24:25] op_sel_hi:[1,0,1]
	v_pk_fma_f32 v[10:11], v[130:131], s[88:89], v[22:23] op_sel_hi:[1,0,1]
	global_store_dwordx4 v[150:151], v[10:13], off offset:576
	s_nop 1
	v_pk_fma_f32 v[12:13], v[144:145], s[88:89], v[162:163] op_sel_hi:[1,0,1]
	v_pk_fma_f32 v[10:11], v[142:143], s[88:89], v[160:161] op_sel_hi:[1,0,1]
	global_store_dwordx4 v[14:15], v[10:13], off
	s_nop 1
	v_pk_fma_f32 v[12:13], v[140:141], s[88:89], v[166:167] op_sel_hi:[1,0,1]
	v_pk_fma_f32 v[10:11], v[138:139], s[88:89], v[164:165] op_sel_hi:[1,0,1]
	global_store_dwordx4 v[14:15], v[10:13], off offset:64
	s_nop 1
	v_pk_fma_f32 v[12:13], v[128:129], s[88:89], v[184:185] op_sel_hi:[1,0,1]
	v_pk_fma_f32 v[10:11], v[126:127], s[88:89], v[182:183] op_sel_hi:[1,0,1]
	global_store_dwordx4 v[14:15], v[10:13], off offset:512
	s_nop 1
	v_pk_fma_f32 v[12:13], v[124:125], s[88:89], v[188:189] op_sel_hi:[1,0,1]
	v_pk_fma_f32 v[10:11], v[122:123], s[88:89], v[186:187] op_sel_hi:[1,0,1]
	global_store_dwordx4 v[14:15], v[10:13], off offset:576
	s_nop 1
	v_or_b32_e32 v10, 32, v8
	v_ashrrev_i32_e32 v11, 31, v10
	v_lshlrev_b64 v[138:139], 13, v[10:11]
	v_lshl_add_u64 v[22:23], v[4:5], 0, v[138:139]
	s_nop 0
	v_or_b32_e32 v8, 48, v8
	v_ashrrev_i32_e32 v9, 31, v8
	v_lshlrev_b64 v[140:141], 13, v[8:9]
	v_lshl_add_u64 v[8:9], v[4:5], 0, v[140:141]
	v_lshl_add_u64 v[8:9], s[80:81], 0, v[138:139]
	s_waitcnt vmcnt(8)
;   DI void operator()(const f32x4 (&acc)[2][2][4][2], const pg8::Unit& u, int wr, int wc, int fr, int fq) const {
;     ...
;       for (int mp = 0; mp < 2; ++mp) {
;         f32x4 xv[2][2][2];
; #pragma unroll
;         for (int mm = 0; mm < 2; ++mm)
; #pragma unroll
;           for (int bj = 0; bj < 2; ++bj)
; #pragma unroll
;             for (int n = 0; n < 2; ++n)
;               xv[mm][bj][n] = *(const f32x4*)(xin + (size_t)(row0 + ai * 128 + (mp * 2 + mm) * 16) * 2048 + col0 + bj * 128 + n * 16);
; #pragma unroll
;         for (int mm = 0; mm < 2; ++mm)
; #pragma unroll
;           for (int bj = 0; bj < 2; ++bj)
; #pragma unroll
;             for (int n = 0; n < 2; ++n)
;               *(f32x4*)(xout + (size_t)(row0 + ai * 128 + (mp * 2 + mm) * 16) * 2048 + col0 + bj * 128 + n * 16) = xv[mm][bj][n] + acc[ai][bj][mp * 2 + mm][n] * sc;
;         asm volatile("" ::: "memory");
	v_add_u32_e32 v134, 128, v214
	v_lshlrev_b32_e32 v134, 13, v134
	v_mov_b32_e32 v135, 0
	v_lshl_add_u64 v[134:135], v[216:217], 0, v[134:135]
	global_load_dwordx4 v[122:125], v[134:135], off
	global_load_dwordx4 v[126:129], v[134:135], off offset:64
	global_load_dwordx4 v[130:133], v[134:135], off offset:512
	s_nop 0
	global_load_dwordx4 v[134:137], v[134:135], off offset:576
	v_add_u32_e32 v160, 144, v214
	v_lshlrev_b32_e32 v160, 13, v160
	v_mov_b32_e32 v161, 0
	v_lshl_add_u64 v[160:161], v[216:217], 0, v[160:161]
	global_load_dwordx4 v[142:145], v[160:161], off
	global_load_dwordx4 v[146:149], v[160:161], off offset:64
	global_load_dwordx4 v[150:153], v[160:161], off offset:512
	s_nop 0
	global_load_dwordx4 v[160:163], v[160:161], off offset:576
	v_pk_fma_f32 v[12:13], v[120:121], s[88:89], v[192:193] op_sel_hi:[1,0,1]
	v_pk_fma_f32 v[10:11], v[118:119], s[88:89], v[190:191] op_sel_hi:[1,0,1]
	v_lshl_add_u64 v[118:119], v[8:9], 0, v[2:3]
	global_store_dwordx4 v[118:119], v[10:13], off
	v_pk_fma_f32 v[8:9], v[114:115], s[88:89], v[194:195] op_sel_hi:[1,0,1]
	s_nop 0
	v_pk_fma_f32 v[10:11], v[116:117], s[88:89], v[196:197] op_sel_hi:[1,0,1]
	global_store_dwordx4 v[118:119], v[8:11], off offset:64
	v_lshl_add_u64 v[12:13], s[80:81], 0, v[140:141]
	v_lshl_add_u64 v[12:13], v[12:13], 0, v[2:3]
	v_pk_fma_f32 v[10:11], v[104:105], s[88:89], v[200:201] op_sel_hi:[1,0,1]
	v_pk_fma_f32 v[8:9], v[102:103], s[88:89], v[198:199] op_sel_hi:[1,0,1]
	global_store_dwordx4 v[118:119], v[8:11], off offset:512
	s_nop 1
	v_pk_fma_f32 v[10:11], v[100:101], s[88:89], v[204:205] op_sel_hi:[1,0,1]
	v_pk_fma_f32 v[8:9], v[98:99], s[88:89], v[202:203] op_sel_hi:[1,0,1]
	global_store_dwordx4 v[118:119], v[8:11], off offset:576
	v_lshl_add_u64 v[24:25], v[6:7], 0, s[60:61]
	v_lshl_add_u64 v[20:21], v[4:5], 0, v[24:25]
	v_pk_fma_f32 v[10:11], v[112:113], s[88:89], v[208:209] op_sel_hi:[1,0,1]
	v_pk_fma_f32 v[8:9], v[110:111], s[88:89], v[206:207] op_sel_hi:[1,0,1]
	global_store_dwordx4 v[12:13], v[8:11], off
	v_lshl_add_u64 v[24:25], s[80:81], 0, v[24:25]
	v_lshl_add_u64 v[24:25], v[24:25], 0, v[2:3]
	v_pk_fma_f32 v[10:11], v[108:109], s[88:89], v[212:213] op_sel_hi:[1,0,1]
	v_pk_fma_f32 v[8:9], v[106:107], s[88:89], v[210:211] op_sel_hi:[1,0,1]
	global_store_dwordx4 v[12:13], v[8:11], off offset:64
	v_lshl_add_u64 v[106:107], v[6:7], 0, s[12:13]
	v_lshl_add_u64 v[102:103], v[4:5], 0, v[106:107]
	v_pk_fma_f32 v[10:11], v[96:97], s[88:89], v[238:239] op_sel_hi:[1,0,1]
	v_pk_fma_f32 v[8:9], v[94:95], s[88:89], v[236:237] op_sel_hi:[1,0,1]
	global_store_dwordx4 v[12:13], v[8:11], off offset:512
	s_mov_b64 s[12:13], 0x140000
	s_nop 0
	v_pk_fma_f32 v[10:11], v[92:93], s[88:89], v[242:243] op_sel_hi:[1,0,1]
	v_pk_fma_f32 v[8:9], v[90:91], s[88:89], v[240:241] op_sel_hi:[1,0,1]
	global_store_dwordx4 v[12:13], v[8:11], off offset:576
	s_nop 0
	s_nop 0
	s_nop 0
	s_waitcnt vmcnt(8)
;   DI void operator()(const f32x4 (&acc)[2][2][4][2], const pg8::Unit& u, int wr, int wc, int fr, int fq) const {
;     ...
;       for (int mp = 0; mp < 2; ++mp) {
;         f32x4 xv[2][2][2];
; #pragma unroll
;         for (int mm = 0; mm < 2; ++mm)
; #pragma unroll
;           for (int bj = 0; bj < 2; ++bj)
; #pragma unroll
;             for (int n = 0; n < 2; ++n)
;               xv[mm][bj][n] = *(const f32x4*)(xin + (size_t)(row0 + ai * 128 + (mp * 2 + mm) * 16) * 2048 + col0 + bj * 128 + n * 16);
; #pragma unroll
;         for (int mm = 0; mm < 2; ++mm)
; #pragma unroll
;           for (int bj = 0; bj < 2; ++bj)
; #pragma unroll
;             for (int n = 0; n < 2; ++n)
;               *(f32x4*)(xout + (size_t)(row0 + ai * 128 + (mp * 2 + mm) * 16) * 2048 + col0 + bj * 128 + n * 16) = xv[mm][bj][n] + acc[ai][bj][mp * 2 + mm][n] * sc;
;         asm volatile("" ::: "memory");
	v_add_u32_e32 v202, 160, v214
	v_lshlrev_b32_e32 v202, 13, v202
	v_mov_b32_e32 v203, 0
	v_lshl_add_u64 v[202:203], v[216:217], 0, v[202:203]
	global_load_dwordx4 v[190:193], v[202:203], off
	global_load_dwordx4 v[194:197], v[202:203], off offset:64
	global_load_dwordx4 v[198:201], v[202:203], off offset:512
	s_nop 0
	global_load_dwordx4 v[202:205], v[202:203], off offset:576
	v_add_u32_e32 v240, 176, v214
	v_lshlrev_b32_e32 v240, 13, v240
	v_mov_b32_e32 v241, 0
	v_lshl_add_u64 v[240:241], v[216:217], 0, v[240:241]
	global_load_dwordx4 v[206:209], v[240:241], off
	global_load_dwordx4 v[210:213], v[240:241], off offset:64
	global_load_dwordx4 v[236:239], v[240:241], off offset:512
	s_nop 0
	global_load_dwordx4 v[240:243], v[240:241], off offset:576
	v_pk_fma_f32 v[10:11], v[88:89], s[88:89], v[124:125] op_sel_hi:[1,0,1]
	v_pk_fma_f32 v[8:9], v[86:87], s[88:89], v[122:123] op_sel_hi:[1,0,1]
	global_store_dwordx4 v[24:25], v[8:11], off
	s_nop 1
	v_pk_fma_f32 v[10:11], v[84:85], s[88:89], v[128:129] op_sel_hi:[1,0,1]
	v_pk_fma_f32 v[8:9], v[82:83], s[88:89], v[126:127] op_sel_hi:[1,0,1]
	global_store_dwordx4 v[24:25], v[8:11], off offset:64
	v_lshl_add_u64 v[12:13], s[80:81], 0, v[106:107]
	v_lshl_add_u64 v[12:13], v[12:13], 0, v[2:3]
	v_pk_fma_f32 v[10:11], v[72:73], s[88:89], v[132:133] op_sel_hi:[1,0,1]
	v_pk_fma_f32 v[8:9], v[70:71], s[88:89], v[130:131] op_sel_hi:[1,0,1]
	global_store_dwordx4 v[24:25], v[8:11], off offset:512
	s_nop 1
	v_pk_fma_f32 v[10:11], v[68:69], s[88:89], v[136:137] op_sel_hi:[1,0,1]
	v_pk_fma_f32 v[8:9], v[66:67], s[88:89], v[134:135] op_sel_hi:[1,0,1]
	global_store_dwordx4 v[24:25], v[8:11], off offset:576
	v_lshl_add_u64 v[24:25], v[6:7], 0, s[12:13]
	v_lshl_add_u64 v[20:21], v[4:5], 0, v[24:25]
	v_pk_fma_f32 v[10:11], v[80:81], s[88:89], v[144:145] op_sel_hi:[1,0,1]
	v_pk_fma_f32 v[8:9], v[78:79], s[88:89], v[142:143] op_sel_hi:[1,0,1]
	global_store_dwordx4 v[12:13], v[8:11], off
	s_mov_b64 s[12:13], 0x160000
	v_lshl_add_u64 v[70:71], v[6:7], 0, s[12:13]
	v_pk_fma_f32 v[10:11], v[76:77], s[88:89], v[148:149] op_sel_hi:[1,0,1]
	v_pk_fma_f32 v[8:9], v[74:75], s[88:89], v[146:147] op_sel_hi:[1,0,1]
	global_store_dwordx4 v[12:13], v[8:11], off offset:64
	v_lshl_add_u64 v[66:67], v[4:5], 0, v[70:71]
	v_lshl_add_u64 v[24:25], s[80:81], 0, v[24:25]
	v_pk_fma_f32 v[10:11], v[64:65], s[88:89], v[152:153] op_sel_hi:[1,0,1]
	v_pk_fma_f32 v[8:9], v[62:63], s[88:89], v[150:151] op_sel_hi:[1,0,1]
	global_store_dwordx4 v[12:13], v[8:11], off offset:512
	v_lshl_add_u64 v[24:25], v[24:25], 0, v[2:3]
	s_mov_b64 s[12:13], s[10:11]
	v_pk_fma_f32 v[10:11], v[60:61], s[88:89], v[162:163] op_sel_hi:[1,0,1]
	v_pk_fma_f32 v[8:9], v[58:59], s[88:89], v[160:161] op_sel_hi:[1,0,1]
	global_store_dwordx4 v[12:13], v[8:11], off offset:576
	s_nop 0
	s_nop 0
	s_nop 0
	s_waitcnt vmcnt(8)
	v_pk_fma_f32 v[10:11], v[56:57], s[88:89], v[192:193] op_sel_hi:[1,0,1]
	v_pk_fma_f32 v[8:9], v[54:55], s[88:89], v[190:191] op_sel_hi:[1,0,1]
	global_store_dwordx4 v[24:25], v[8:11], off
	v_pk_fma_f32 v[6:7], v[48:49], s[88:89], v[208:209] op_sel_hi:[1,0,1]
	v_pk_fma_f32 v[4:5], v[46:47], s[88:89], v[206:207] op_sel_hi:[1,0,1]
	v_pk_fma_f32 v[10:11], v[52:53], s[88:89], v[196:197] op_sel_hi:[1,0,1]
	v_pk_fma_f32 v[8:9], v[50:51], s[88:89], v[194:195] op_sel_hi:[1,0,1]
	global_store_dwordx4 v[24:25], v[8:11], off offset:64
	s_nop 1
	v_pk_fma_f32 v[10:11], v[40:41], s[88:89], v[200:201] op_sel_hi:[1,0,1]
	v_pk_fma_f32 v[8:9], v[38:39], s[88:89], v[198:199] op_sel_hi:[1,0,1]
	global_store_dwordx4 v[24:25], v[8:11], off offset:512
	s_nop 1
	v_pk_fma_f32 v[10:11], v[36:37], s[88:89], v[204:205] op_sel_hi:[1,0,1]
	v_pk_fma_f32 v[8:9], v[34:35], s[88:89], v[202:203] op_sel_hi:[1,0,1]
	global_store_dwordx4 v[24:25], v[8:11], off offset:576
	s_nop 1
	v_lshl_add_u64 v[8:9], s[80:81], 0, v[70:71]
	v_lshl_add_u64 v[8:9], v[8:9], 0, v[2:3]
	global_store_dwordx4 v[8:9], v[4:7], off
	v_pk_fma_f32 v[2:3], v[42:43], s[88:89], v[210:211] op_sel_hi:[1,0,1]
	s_nop 0
	v_pk_fma_f32 v[4:5], v[44:45], s[88:89], v[212:213] op_sel_hi:[1,0,1]
	global_store_dwordx4 v[8:9], v[2:5], off offset:64
	s_nop 1
	v_pk_fma_f32 v[4:5], v[32:33], s[88:89], v[238:239] op_sel_hi:[1,0,1]
	v_pk_fma_f32 v[2:3], v[30:31], s[88:89], v[236:237] op_sel_hi:[1,0,1]
	global_store_dwordx4 v[8:9], v[2:5], off offset:512
	s_nop 1
	v_pk_fma_f32 v[4:5], v[28:29], s[88:89], v[242:243] op_sel_hi:[1,0,1]
	v_pk_fma_f32 v[2:3], v[26:27], s[88:89], v[240:241] op_sel_hi:[1,0,1]
	global_store_dwordx4 v[8:9], v[2:5], off offset:576
	s_cbranch_vccz .LBB0_1532
	s_waitcnt vmcnt(0)
	s_cmpk_gt_u32 s22, 0xff
	v_readlane_b32 s28, v254, 27
	v_readlane_b32 s29, v254, 28
	s_cbranch_scc1 .LBB0_1547
	s_barrier
